# P1 plain/sigmoid tiles: w_in columns remapped so each wave owns whole 128-byte lines; DPP half-swap + full-line stores
# speedup vs baseline: 1.0171x; 1.0027x over previous
.LBB0_66:
	s_andn2_saveexec_b64 s[12:13], s[6:7]
	s_cbranch_execz .LBB0_55
	v_mul_hi_i32 v6, v98, s23
	v_lshrrev_b32_e32 v16, 31, v6
	v_ashrrev_i32_e32 v6, 5, v6
	v_add_u32_e32 v16, v6, v16
	v_mul_lo_u32 v6, v16, s22
	v_add_u32_e32 v19, v64, v6
	v_add_u32_e32 v17, 0xe00, v19
	v_add_u32_e32 v18, v17, v1
	v_cmp_lt_i32_e32 vcc, s24, v18
	s_and_saveexec_b64 s[2:3], vcc
	s_xor_b64 s[2:3], exec, s[2:3]
	s_cbranch_execz .LBB0_71
	v_cmp_lt_u32_e32 vcc, s25, v17
	s_and_saveexec_b64 s[6:7], vcc
	v_lshrrev_b32_e32 v17, 1, v19
	v_and_b32_e32 v17, 0x7fffff80, v17
	v_and_b32_e32 v18, 0x7b, v18
	v_and_or_b32 v19, v98, 4, v63
	v_add3_u32 v18, v19, v18, v17
	s_xor_b64 exec, exec, s[6:7]
	v_bfe_u32 v17, v18, 5, 2
	v_bfe_u32 v19, v18, 7, 1
	v_and_b32_e32 v18, 0xffffff1f, v18
	v_lshl_or_b32 v18, v17, 6, v18
	v_lshl_or_b32 v18, v19, 5, v18
	s_mov_b64 exec, s[6:7]

.LBB0_221:
	s_andn2_b64 vcc, exec, s[2:3]
	s_cbranch_vccnz .LBB0_255
	v_readfirstlane_b32 s10, v214
	v_readlane_b32 s2, v246, 26
	v_readlane_b32 s3, v246, 27
	v_and_b32_e32 v148, 7, v214
	v_bfe_u32 v149, v214, 3, 1
	v_bfe_u32 v150, v214, 4, 2
	v_mul_u32_u24_e32 v148, 0x2c00, v148
	v_lshl_add_u32 v148, v149, 6, v148
	v_lshl_add_u32 v148, v150, 4, v148
	v_add_u32_e32 v149, 0x16000, v148
	s_lshr_b32 s11, s10, 8
	s_lshl_b32 s11, s11, 6
	s_lshl_b32 s66, s0, 8
	s_add_u32 s11, s11, s66
	s_mul_i32 s11, s11, 0x2c00
	s_bfe_u32 s10, s10, 0x20006
	s_lshl_b32 s10, s10, 7
	s_lshl_b32 s66, s4, 9
	s_add_u32 s10, s10, s66
	s_add_u32 s66, s2, s11
	s_addc_u32 s67, s3, 0
	s_add_u32 s66, s66, s10
	s_addc_u32 s67, s67, 0
	s_mov_b32 s68, 0xbfb8aa3b
	s_cmp_gt_u32 s4, 11
	s_cbranch_scc1 .Lp1f_sig
	v_cvt_pk_bf16_f32 v124, v124, v125
	v_cvt_pk_bf16_f32 v125, v126, v127
	v_cvt_pk_bf16_f32 v126, v120, v121
	v_cvt_pk_bf16_f32 v127, v122, v123
	v_cvt_pk_bf16_f32 v116, v116, v117
	v_cvt_pk_bf16_f32 v117, v118, v119
	v_cvt_pk_bf16_f32 v118, v112, v113
	v_cvt_pk_bf16_f32 v119, v114, v115
	v_mov_b32_dpp v120, v116 row_ror:8 row_mask:0xf bank_mask:0xf
	v_mov_b32_dpp v121, v117 row_ror:8 row_mask:0xf bank_mask:0xf
	v_mov_b32_dpp v122, v118 row_ror:8 row_mask:0xf bank_mask:0xf
	v_mov_b32_dpp v123, v119 row_ror:8 row_mask:0xf bank_mask:0xf
	v_mov_b32_dpp v116, v124 row_ror:8 row_mask:0xf bank_mask:0x3
	v_mov_b32_dpp v117, v125 row_ror:8 row_mask:0xf bank_mask:0x3
	v_mov_b32_dpp v118, v126 row_ror:8 row_mask:0xf bank_mask:0x3
	v_mov_b32_dpp v119, v127 row_ror:8 row_mask:0xf bank_mask:0x3
	v_mov_b32_dpp v124, v120 quad_perm:[0,1,2,3] row_mask:0xf bank_mask:0xc
	v_mov_b32_dpp v125, v121 quad_perm:[0,1,2,3] row_mask:0xf bank_mask:0xc
	v_mov_b32_dpp v126, v122 quad_perm:[0,1,2,3] row_mask:0xf bank_mask:0xc
	v_mov_b32_dpp v127, v123 quad_perm:[0,1,2,3] row_mask:0xf bank_mask:0xc
	global_store_dwordx4 v148, v[124:127], s[66:67] nt
	global_store_dwordx4 v149, v[116:119], s[66:67] nt
	s_add_u32 s66, s66, 0x2c000
	s_addc_u32 s67, s67, 0
	v_cvt_pk_bf16_f32 v108, v108, v109
	v_cvt_pk_bf16_f32 v109, v110, v111
	v_cvt_pk_bf16_f32 v110, v104, v105
	v_cvt_pk_bf16_f32 v111, v106, v107
	v_cvt_pk_bf16_f32 v100, v100, v101
	v_cvt_pk_bf16_f32 v101, v102, v103
	v_cvt_pk_bf16_f32 v102, v96, v97
	v_cvt_pk_bf16_f32 v103, v98, v99
	v_mov_b32_dpp v104, v100 row_ror:8 row_mask:0xf bank_mask:0xf
	v_mov_b32_dpp v105, v101 row_ror:8 row_mask:0xf bank_mask:0xf
	v_mov_b32_dpp v106, v102 row_ror:8 row_mask:0xf bank_mask:0xf
	v_mov_b32_dpp v107, v103 row_ror:8 row_mask:0xf bank_mask:0xf
	v_mov_b32_dpp v100, v108 row_ror:8 row_mask:0xf bank_mask:0x3
	v_mov_b32_dpp v101, v109 row_ror:8 row_mask:0xf bank_mask:0x3
	v_mov_b32_dpp v102, v110 row_ror:8 row_mask:0xf bank_mask:0x3
	v_mov_b32_dpp v103, v111 row_ror:8 row_mask:0xf bank_mask:0x3
	v_mov_b32_dpp v108, v104 quad_perm:[0,1,2,3] row_mask:0xf bank_mask:0xc
	v_mov_b32_dpp v109, v105 quad_perm:[0,1,2,3] row_mask:0xf bank_mask:0xc
	v_mov_b32_dpp v110, v106 quad_perm:[0,1,2,3] row_mask:0xf bank_mask:0xc
	v_mov_b32_dpp v111, v107 quad_perm:[0,1,2,3] row_mask:0xf bank_mask:0xc
	global_store_dwordx4 v148, v[108:111], s[66:67] nt
	global_store_dwordx4 v149, v[100:103], s[66:67] nt
	s_add_u32 s66, s66, 0x2c000
	s_addc_u32 s67, s67, 0
	v_cvt_pk_bf16_f32 v92, v92, v93
	v_cvt_pk_bf16_f32 v93, v94, v95
	v_cvt_pk_bf16_f32 v94, v88, v89
	v_cvt_pk_bf16_f32 v95, v90, v91
	v_cvt_pk_bf16_f32 v84, v84, v85
	v_cvt_pk_bf16_f32 v85, v86, v87
	v_cvt_pk_bf16_f32 v86, v80, v81
	v_cvt_pk_bf16_f32 v87, v82, v83
	v_mov_b32_dpp v88, v84 row_ror:8 row_mask:0xf bank_mask:0xf
	v_mov_b32_dpp v89, v85 row_ror:8 row_mask:0xf bank_mask:0xf
	v_mov_b32_dpp v90, v86 row_ror:8 row_mask:0xf bank_mask:0xf
	v_mov_b32_dpp v91, v87 row_ror:8 row_mask:0xf bank_mask:0xf
	v_mov_b32_dpp v84, v92 row_ror:8 row_mask:0xf bank_mask:0x3
	v_mov_b32_dpp v85, v93 row_ror:8 row_mask:0xf bank_mask:0x3
	v_mov_b32_dpp v86, v94 row_ror:8 row_mask:0xf bank_mask:0x3
	v_mov_b32_dpp v87, v95 row_ror:8 row_mask:0xf bank_mask:0x3
	v_mov_b32_dpp v92, v88 quad_perm:[0,1,2,3] row_mask:0xf bank_mask:0xc
	v_mov_b32_dpp v93, v89 quad_perm:[0,1,2,3] row_mask:0xf bank_mask:0xc
	v_mov_b32_dpp v94, v90 quad_perm:[0,1,2,3] row_mask:0xf bank_mask:0xc
	v_mov_b32_dpp v95, v91 quad_perm:[0,1,2,3] row_mask:0xf bank_mask:0xc
	global_store_dwordx4 v148, v[92:95], s[66:67] nt
	global_store_dwordx4 v149, v[84:87], s[66:67] nt
	s_add_u32 s66, s66, 0x2c000
	s_addc_u32 s67, s67, 0
	v_cvt_pk_bf16_f32 v76, v76, v77
	v_cvt_pk_bf16_f32 v77, v78, v79
	v_cvt_pk_bf16_f32 v78, v72, v73
	v_cvt_pk_bf16_f32 v79, v74, v75
	v_cvt_pk_bf16_f32 v68, v68, v69
	v_cvt_pk_bf16_f32 v69, v70, v71
	v_cvt_pk_bf16_f32 v70, v64, v65
	v_cvt_pk_bf16_f32 v71, v66, v67
	v_mov_b32_dpp v72, v68 row_ror:8 row_mask:0xf bank_mask:0xf
	v_mov_b32_dpp v73, v69 row_ror:8 row_mask:0xf bank_mask:0xf
	v_mov_b32_dpp v74, v70 row_ror:8 row_mask:0xf bank_mask:0xf
	v_mov_b32_dpp v75, v71 row_ror:8 row_mask:0xf bank_mask:0xf
	v_mov_b32_dpp v68, v76 row_ror:8 row_mask:0xf bank_mask:0x3
	v_mov_b32_dpp v69, v77 row_ror:8 row_mask:0xf bank_mask:0x3
	v_mov_b32_dpp v70, v78 row_ror:8 row_mask:0xf bank_mask:0x3
	v_mov_b32_dpp v71, v79 row_ror:8 row_mask:0xf bank_mask:0x3
	v_mov_b32_dpp v76, v72 quad_perm:[0,1,2,3] row_mask:0xf bank_mask:0xc
	v_mov_b32_dpp v77, v73 quad_perm:[0,1,2,3] row_mask:0xf bank_mask:0xc
	v_mov_b32_dpp v78, v74 quad_perm:[0,1,2,3] row_mask:0xf bank_mask:0xc
	v_mov_b32_dpp v79, v75 quad_perm:[0,1,2,3] row_mask:0xf bank_mask:0xc
	global_store_dwordx4 v148, v[76:79], s[66:67] nt
	global_store_dwordx4 v149, v[68:71], s[66:67] nt
	s_add_u32 s66, s66, 0xdc000
	s_addc_u32 s67, s67, 0
	v_cvt_pk_bf16_f32 v60, v60, v61
	v_cvt_pk_bf16_f32 v61, v62, v63
	v_cvt_pk_bf16_f32 v62, v56, v57
	v_cvt_pk_bf16_f32 v63, v58, v59
	v_cvt_pk_bf16_f32 v52, v52, v53
	v_cvt_pk_bf16_f32 v53, v54, v55
	v_cvt_pk_bf16_f32 v54, v48, v49
	v_cvt_pk_bf16_f32 v55, v50, v51
	v_mov_b32_dpp v56, v52 row_ror:8 row_mask:0xf bank_mask:0xf
	v_mov_b32_dpp v57, v53 row_ror:8 row_mask:0xf bank_mask:0xf
	v_mov_b32_dpp v58, v54 row_ror:8 row_mask:0xf bank_mask:0xf
	v_mov_b32_dpp v59, v55 row_ror:8 row_mask:0xf bank_mask:0xf
	v_mov_b32_dpp v52, v60 row_ror:8 row_mask:0xf bank_mask:0x3
	v_mov_b32_dpp v53, v61 row_ror:8 row_mask:0xf bank_mask:0x3
	v_mov_b32_dpp v54, v62 row_ror:8 row_mask:0xf bank_mask:0x3
	v_mov_b32_dpp v55, v63 row_ror:8 row_mask:0xf bank_mask:0x3
	v_mov_b32_dpp v60, v56 quad_perm:[0,1,2,3] row_mask:0xf bank_mask:0xc
	v_mov_b32_dpp v61, v57 quad_perm:[0,1,2,3] row_mask:0xf bank_mask:0xc
	v_mov_b32_dpp v62, v58 quad_perm:[0,1,2,3] row_mask:0xf bank_mask:0xc
	v_mov_b32_dpp v63, v59 quad_perm:[0,1,2,3] row_mask:0xf bank_mask:0xc
	global_store_dwordx4 v148, v[60:63], s[66:67] nt
	global_store_dwordx4 v149, v[52:55], s[66:67] nt
	s_add_u32 s66, s66, 0x2c000
	s_addc_u32 s67, s67, 0
	v_cvt_pk_bf16_f32 v44, v44, v45
	v_cvt_pk_bf16_f32 v45, v46, v47
	v_cvt_pk_bf16_f32 v46, v40, v41
	v_cvt_pk_bf16_f32 v47, v42, v43
	v_cvt_pk_bf16_f32 v36, v36, v37
	v_cvt_pk_bf16_f32 v37, v38, v39
	v_cvt_pk_bf16_f32 v38, v32, v33
	v_cvt_pk_bf16_f32 v39, v34, v35
	v_mov_b32_dpp v40, v36 row_ror:8 row_mask:0xf bank_mask:0xf
	v_mov_b32_dpp v41, v37 row_ror:8 row_mask:0xf bank_mask:0xf
	v_mov_b32_dpp v42, v38 row_ror:8 row_mask:0xf bank_mask:0xf
	v_mov_b32_dpp v43, v39 row_ror:8 row_mask:0xf bank_mask:0xf
	v_mov_b32_dpp v36, v44 row_ror:8 row_mask:0xf bank_mask:0x3
	v_mov_b32_dpp v37, v45 row_ror:8 row_mask:0xf bank_mask:0x3
	v_mov_b32_dpp v38, v46 row_ror:8 row_mask:0xf bank_mask:0x3
	v_mov_b32_dpp v39, v47 row_ror:8 row_mask:0xf bank_mask:0x3
	v_mov_b32_dpp v44, v40 quad_perm:[0,1,2,3] row_mask:0xf bank_mask:0xc
	v_mov_b32_dpp v45, v41 quad_perm:[0,1,2,3] row_mask:0xf bank_mask:0xc
	v_mov_b32_dpp v46, v42 quad_perm:[0,1,2,3] row_mask:0xf bank_mask:0xc
	v_mov_b32_dpp v47, v43 quad_perm:[0,1,2,3] row_mask:0xf bank_mask:0xc
	global_store_dwordx4 v148, v[44:47], s[66:67] nt
	global_store_dwordx4 v149, v[36:39], s[66:67] nt
	s_add_u32 s66, s66, 0x2c000
	s_addc_u32 s67, s67, 0
	v_cvt_pk_bf16_f32 v28, v28, v29
	v_cvt_pk_bf16_f32 v29, v30, v31
	v_cvt_pk_bf16_f32 v30, v24, v25
	v_cvt_pk_bf16_f32 v31, v26, v27
	v_cvt_pk_bf16_f32 v20, v20, v21
	v_cvt_pk_bf16_f32 v21, v22, v23
	v_cvt_pk_bf16_f32 v22, v16, v17
	v_cvt_pk_bf16_f32 v23, v18, v19
	v_mov_b32_dpp v24, v20 row_ror:8 row_mask:0xf bank_mask:0xf
	v_mov_b32_dpp v25, v21 row_ror:8 row_mask:0xf bank_mask:0xf
	v_mov_b32_dpp v26, v22 row_ror:8 row_mask:0xf bank_mask:0xf
	v_mov_b32_dpp v27, v23 row_ror:8 row_mask:0xf bank_mask:0xf
	v_mov_b32_dpp v20, v28 row_ror:8 row_mask:0xf bank_mask:0x3
	v_mov_b32_dpp v21, v29 row_ror:8 row_mask:0xf bank_mask:0x3
	v_mov_b32_dpp v22, v30 row_ror:8 row_mask:0xf bank_mask:0x3
	v_mov_b32_dpp v23, v31 row_ror:8 row_mask:0xf bank_mask:0x3
	v_mov_b32_dpp v28, v24 quad_perm:[0,1,2,3] row_mask:0xf bank_mask:0xc
	v_mov_b32_dpp v29, v25 quad_perm:[0,1,2,3] row_mask:0xf bank_mask:0xc
	v_mov_b32_dpp v30, v26 quad_perm:[0,1,2,3] row_mask:0xf bank_mask:0xc
	v_mov_b32_dpp v31, v27 quad_perm:[0,1,2,3] row_mask:0xf bank_mask:0xc
	global_store_dwordx4 v148, v[28:31], s[66:67] nt
	global_store_dwordx4 v149, v[20:23], s[66:67] nt
	s_add_u32 s66, s66, 0x2c000
	s_addc_u32 s67, s67, 0
	v_cvt_pk_bf16_f32 v12, v12, v13
	v_cvt_pk_bf16_f32 v13, v14, v15
	v_cvt_pk_bf16_f32 v14, v8, v9
	v_cvt_pk_bf16_f32 v15, v10, v11
	v_cvt_pk_bf16_f32 v4, v4, v5
	v_cvt_pk_bf16_f32 v5, v6, v7
	v_cvt_pk_bf16_f32 v6, v0, v1
	v_cvt_pk_bf16_f32 v7, v2, v3
	v_mov_b32_dpp v8, v4 row_ror:8 row_mask:0xf bank_mask:0xf
	v_mov_b32_dpp v9, v5 row_ror:8 row_mask:0xf bank_mask:0xf
	v_mov_b32_dpp v10, v6 row_ror:8 row_mask:0xf bank_mask:0xf
	v_mov_b32_dpp v11, v7 row_ror:8 row_mask:0xf bank_mask:0xf
	v_mov_b32_dpp v4, v12 row_ror:8 row_mask:0xf bank_mask:0x3
	v_mov_b32_dpp v5, v13 row_ror:8 row_mask:0xf bank_mask:0x3
	v_mov_b32_dpp v6, v14 row_ror:8 row_mask:0xf bank_mask:0x3
	v_mov_b32_dpp v7, v15 row_ror:8 row_mask:0xf bank_mask:0x3
	v_mov_b32_dpp v12, v8 quad_perm:[0,1,2,3] row_mask:0xf bank_mask:0xc
	v_mov_b32_dpp v13, v9 quad_perm:[0,1,2,3] row_mask:0xf bank_mask:0xc
	v_mov_b32_dpp v14, v10 quad_perm:[0,1,2,3] row_mask:0xf bank_mask:0xc
	v_mov_b32_dpp v15, v11 quad_perm:[0,1,2,3] row_mask:0xf bank_mask:0xc
	global_store_dwordx4 v148, v[12:15], s[66:67] nt
	global_store_dwordx4 v149, v[4:7], s[66:67] nt
	s_branch .LBB0_255
.Lp1f_sig:
	v_pk_mul_f32 v[112:113], v[112:113], s[68:69] op_sel_hi:[1,0]
	v_pk_mul_f32 v[114:115], v[114:115], s[68:69] op_sel_hi:[1,0]
	v_pk_mul_f32 v[116:117], v[116:117], s[68:69] op_sel_hi:[1,0]
	v_pk_mul_f32 v[118:119], v[118:119], s[68:69] op_sel_hi:[1,0]
	v_pk_mul_f32 v[120:121], v[120:121], s[68:69] op_sel_hi:[1,0]
	v_pk_mul_f32 v[122:123], v[122:123], s[68:69] op_sel_hi:[1,0]
	v_pk_mul_f32 v[124:125], v[124:125], s[68:69] op_sel_hi:[1,0]
	v_pk_mul_f32 v[126:127], v[126:127], s[68:69] op_sel_hi:[1,0]
	v_exp_f32_e32 v112, v112
	v_exp_f32_e32 v113, v113
	v_exp_f32_e32 v114, v114
	v_exp_f32_e32 v115, v115
	v_exp_f32_e32 v116, v116
	v_exp_f32_e32 v117, v117
	v_exp_f32_e32 v118, v118
	v_exp_f32_e32 v119, v119
	v_exp_f32_e32 v120, v120
	v_exp_f32_e32 v121, v121
	v_exp_f32_e32 v122, v122
	v_exp_f32_e32 v123, v123
	v_exp_f32_e32 v124, v124
	v_exp_f32_e32 v125, v125
	v_exp_f32_e32 v126, v126
	v_exp_f32_e32 v127, v127
	v_pk_add_f32 v[112:113], v[112:113], 1.0 op_sel_hi:[1,0]
	v_pk_add_f32 v[114:115], v[114:115], 1.0 op_sel_hi:[1,0]
	v_pk_add_f32 v[116:117], v[116:117], 1.0 op_sel_hi:[1,0]
	v_pk_add_f32 v[118:119], v[118:119], 1.0 op_sel_hi:[1,0]
	v_pk_add_f32 v[120:121], v[120:121], 1.0 op_sel_hi:[1,0]
	v_pk_add_f32 v[122:123], v[122:123], 1.0 op_sel_hi:[1,0]
	v_pk_add_f32 v[124:125], v[124:125], 1.0 op_sel_hi:[1,0]
	v_pk_add_f32 v[126:127], v[126:127], 1.0 op_sel_hi:[1,0]
	v_rcp_f32_e32 v112, v112
	v_rcp_f32_e32 v113, v113
	v_rcp_f32_e32 v114, v114
	v_rcp_f32_e32 v115, v115
	v_rcp_f32_e32 v116, v116
	v_rcp_f32_e32 v117, v117
	v_rcp_f32_e32 v118, v118
	v_rcp_f32_e32 v119, v119
	v_rcp_f32_e32 v120, v120
	v_rcp_f32_e32 v121, v121
	v_rcp_f32_e32 v122, v122
	v_rcp_f32_e32 v123, v123
	v_rcp_f32_e32 v124, v124
	v_rcp_f32_e32 v125, v125
	v_rcp_f32_e32 v126, v126
	v_rcp_f32_e32 v127, v127
	v_cvt_pk_bf16_f32 v124, v124, v125
	v_cvt_pk_bf16_f32 v125, v126, v127
	v_cvt_pk_bf16_f32 v126, v120, v121
	v_cvt_pk_bf16_f32 v127, v122, v123
	v_cvt_pk_bf16_f32 v116, v116, v117
	v_cvt_pk_bf16_f32 v117, v118, v119
	v_cvt_pk_bf16_f32 v118, v112, v113
	v_cvt_pk_bf16_f32 v119, v114, v115
	v_mov_b32_dpp v120, v116 row_ror:8 row_mask:0xf bank_mask:0xf
	v_mov_b32_dpp v121, v117 row_ror:8 row_mask:0xf bank_mask:0xf
	v_mov_b32_dpp v122, v118 row_ror:8 row_mask:0xf bank_mask:0xf
	v_mov_b32_dpp v123, v119 row_ror:8 row_mask:0xf bank_mask:0xf
	v_mov_b32_dpp v116, v124 row_ror:8 row_mask:0xf bank_mask:0x3
	v_mov_b32_dpp v117, v125 row_ror:8 row_mask:0xf bank_mask:0x3
	v_mov_b32_dpp v118, v126 row_ror:8 row_mask:0xf bank_mask:0x3
	v_mov_b32_dpp v119, v127 row_ror:8 row_mask:0xf bank_mask:0x3
	v_mov_b32_dpp v124, v120 quad_perm:[0,1,2,3] row_mask:0xf bank_mask:0xc
	v_mov_b32_dpp v125, v121 quad_perm:[0,1,2,3] row_mask:0xf bank_mask:0xc
	v_mov_b32_dpp v126, v122 quad_perm:[0,1,2,3] row_mask:0xf bank_mask:0xc
	v_mov_b32_dpp v127, v123 quad_perm:[0,1,2,3] row_mask:0xf bank_mask:0xc
	global_store_dwordx4 v148, v[124:127], s[66:67] nt
	global_store_dwordx4 v149, v[116:119], s[66:67] nt
	s_add_u32 s66, s66, 0x2c000
	s_addc_u32 s67, s67, 0
	v_pk_mul_f32 v[96:97], v[96:97], s[68:69] op_sel_hi:[1,0]
	v_pk_mul_f32 v[98:99], v[98:99], s[68:69] op_sel_hi:[1,0]
	v_pk_mul_f32 v[100:101], v[100:101], s[68:69] op_sel_hi:[1,0]
	v_pk_mul_f32 v[102:103], v[102:103], s[68:69] op_sel_hi:[1,0]
	v_pk_mul_f32 v[104:105], v[104:105], s[68:69] op_sel_hi:[1,0]
	v_pk_mul_f32 v[106:107], v[106:107], s[68:69] op_sel_hi:[1,0]
	v_pk_mul_f32 v[108:109], v[108:109], s[68:69] op_sel_hi:[1,0]
	v_pk_mul_f32 v[110:111], v[110:111], s[68:69] op_sel_hi:[1,0]
	v_exp_f32_e32 v96, v96
	v_exp_f32_e32 v97, v97
	v_exp_f32_e32 v98, v98
	v_exp_f32_e32 v99, v99
	v_exp_f32_e32 v100, v100
	v_exp_f32_e32 v101, v101
	v_exp_f32_e32 v102, v102
	v_exp_f32_e32 v103, v103
	v_exp_f32_e32 v104, v104
	v_exp_f32_e32 v105, v105
	v_exp_f32_e32 v106, v106
	v_exp_f32_e32 v107, v107
	v_exp_f32_e32 v108, v108
	v_exp_f32_e32 v109, v109
	v_exp_f32_e32 v110, v110
	v_exp_f32_e32 v111, v111
	v_pk_add_f32 v[96:97], v[96:97], 1.0 op_sel_hi:[1,0]
	v_pk_add_f32 v[98:99], v[98:99], 1.0 op_sel_hi:[1,0]
	v_pk_add_f32 v[100:101], v[100:101], 1.0 op_sel_hi:[1,0]
	v_pk_add_f32 v[102:103], v[102:103], 1.0 op_sel_hi:[1,0]
	v_pk_add_f32 v[104:105], v[104:105], 1.0 op_sel_hi:[1,0]
	v_pk_add_f32 v[106:107], v[106:107], 1.0 op_sel_hi:[1,0]
	v_pk_add_f32 v[108:109], v[108:109], 1.0 op_sel_hi:[1,0]
	v_pk_add_f32 v[110:111], v[110:111], 1.0 op_sel_hi:[1,0]
	v_rcp_f32_e32 v96, v96
	v_rcp_f32_e32 v97, v97
	v_rcp_f32_e32 v98, v98
	v_rcp_f32_e32 v99, v99
	v_rcp_f32_e32 v100, v100
	v_rcp_f32_e32 v101, v101
	v_rcp_f32_e32 v102, v102
	v_rcp_f32_e32 v103, v103
	v_rcp_f32_e32 v104, v104
	v_rcp_f32_e32 v105, v105
	v_rcp_f32_e32 v106, v106
	v_rcp_f32_e32 v107, v107
	v_rcp_f32_e32 v108, v108
	v_rcp_f32_e32 v109, v109
	v_rcp_f32_e32 v110, v110
	v_rcp_f32_e32 v111, v111
	v_cvt_pk_bf16_f32 v108, v108, v109
	v_cvt_pk_bf16_f32 v109, v110, v111
	v_cvt_pk_bf16_f32 v110, v104, v105
	v_cvt_pk_bf16_f32 v111, v106, v107
	v_cvt_pk_bf16_f32 v100, v100, v101
	v_cvt_pk_bf16_f32 v101, v102, v103
	v_cvt_pk_bf16_f32 v102, v96, v97
	v_cvt_pk_bf16_f32 v103, v98, v99
	v_mov_b32_dpp v104, v100 row_ror:8 row_mask:0xf bank_mask:0xf
	v_mov_b32_dpp v105, v101 row_ror:8 row_mask:0xf bank_mask:0xf
	v_mov_b32_dpp v106, v102 row_ror:8 row_mask:0xf bank_mask:0xf
	v_mov_b32_dpp v107, v103 row_ror:8 row_mask:0xf bank_mask:0xf
	v_mov_b32_dpp v100, v108 row_ror:8 row_mask:0xf bank_mask:0x3
	v_mov_b32_dpp v101, v109 row_ror:8 row_mask:0xf bank_mask:0x3
	v_mov_b32_dpp v102, v110 row_ror:8 row_mask:0xf bank_mask:0x3
	v_mov_b32_dpp v103, v111 row_ror:8 row_mask:0xf bank_mask:0x3
	v_mov_b32_dpp v108, v104 quad_perm:[0,1,2,3] row_mask:0xf bank_mask:0xc
	v_mov_b32_dpp v109, v105 quad_perm:[0,1,2,3] row_mask:0xf bank_mask:0xc
	v_mov_b32_dpp v110, v106 quad_perm:[0,1,2,3] row_mask:0xf bank_mask:0xc
	v_mov_b32_dpp v111, v107 quad_perm:[0,1,2,3] row_mask:0xf bank_mask:0xc
	global_store_dwordx4 v148, v[108:111], s[66:67] nt
	global_store_dwordx4 v149, v[100:103], s[66:67] nt
	s_add_u32 s66, s66, 0x2c000
	s_addc_u32 s67, s67, 0
	v_pk_mul_f32 v[80:81], v[80:81], s[68:69] op_sel_hi:[1,0]
	v_pk_mul_f32 v[82:83], v[82:83], s[68:69] op_sel_hi:[1,0]
	v_pk_mul_f32 v[84:85], v[84:85], s[68:69] op_sel_hi:[1,0]
	v_pk_mul_f32 v[86:87], v[86:87], s[68:69] op_sel_hi:[1,0]
	v_pk_mul_f32 v[88:89], v[88:89], s[68:69] op_sel_hi:[1,0]
	v_pk_mul_f32 v[90:91], v[90:91], s[68:69] op_sel_hi:[1,0]
	v_pk_mul_f32 v[92:93], v[92:93], s[68:69] op_sel_hi:[1,0]
	v_pk_mul_f32 v[94:95], v[94:95], s[68:69] op_sel_hi:[1,0]
	v_exp_f32_e32 v80, v80
	v_exp_f32_e32 v81, v81
	v_exp_f32_e32 v82, v82
	v_exp_f32_e32 v83, v83
	v_exp_f32_e32 v84, v84
	v_exp_f32_e32 v85, v85
	v_exp_f32_e32 v86, v86
	v_exp_f32_e32 v87, v87
	v_exp_f32_e32 v88, v88
	v_exp_f32_e32 v89, v89
	v_exp_f32_e32 v90, v90
	v_exp_f32_e32 v91, v91
	v_exp_f32_e32 v92, v92
	v_exp_f32_e32 v93, v93
	v_exp_f32_e32 v94, v94
	v_exp_f32_e32 v95, v95
	v_pk_add_f32 v[80:81], v[80:81], 1.0 op_sel_hi:[1,0]
	v_pk_add_f32 v[82:83], v[82:83], 1.0 op_sel_hi:[1,0]
	v_pk_add_f32 v[84:85], v[84:85], 1.0 op_sel_hi:[1,0]
	v_pk_add_f32 v[86:87], v[86:87], 1.0 op_sel_hi:[1,0]
	v_pk_add_f32 v[88:89], v[88:89], 1.0 op_sel_hi:[1,0]
	v_pk_add_f32 v[90:91], v[90:91], 1.0 op_sel_hi:[1,0]
	v_pk_add_f32 v[92:93], v[92:93], 1.0 op_sel_hi:[1,0]
	v_pk_add_f32 v[94:95], v[94:95], 1.0 op_sel_hi:[1,0]
	v_rcp_f32_e32 v80, v80
	v_rcp_f32_e32 v81, v81
	v_rcp_f32_e32 v82, v82
	v_rcp_f32_e32 v83, v83
	v_rcp_f32_e32 v84, v84
	v_rcp_f32_e32 v85, v85
	v_rcp_f32_e32 v86, v86
	v_rcp_f32_e32 v87, v87
	v_rcp_f32_e32 v88, v88
	v_rcp_f32_e32 v89, v89
	v_rcp_f32_e32 v90, v90
	v_rcp_f32_e32 v91, v91
	v_rcp_f32_e32 v92, v92
	v_rcp_f32_e32 v93, v93
	v_rcp_f32_e32 v94, v94
	v_rcp_f32_e32 v95, v95
	v_cvt_pk_bf16_f32 v92, v92, v93
	v_cvt_pk_bf16_f32 v93, v94, v95
	v_cvt_pk_bf16_f32 v94, v88, v89
	v_cvt_pk_bf16_f32 v95, v90, v91
	v_cvt_pk_bf16_f32 v84, v84, v85
	v_cvt_pk_bf16_f32 v85, v86, v87
	v_cvt_pk_bf16_f32 v86, v80, v81
	v_cvt_pk_bf16_f32 v87, v82, v83
	v_mov_b32_dpp v88, v84 row_ror:8 row_mask:0xf bank_mask:0xf
	v_mov_b32_dpp v89, v85 row_ror:8 row_mask:0xf bank_mask:0xf
	v_mov_b32_dpp v90, v86 row_ror:8 row_mask:0xf bank_mask:0xf
	v_mov_b32_dpp v91, v87 row_ror:8 row_mask:0xf bank_mask:0xf
	v_mov_b32_dpp v84, v92 row_ror:8 row_mask:0xf bank_mask:0x3
	v_mov_b32_dpp v85, v93 row_ror:8 row_mask:0xf bank_mask:0x3
	v_mov_b32_dpp v86, v94 row_ror:8 row_mask:0xf bank_mask:0x3
	v_mov_b32_dpp v87, v95 row_ror:8 row_mask:0xf bank_mask:0x3
	v_mov_b32_dpp v92, v88 quad_perm:[0,1,2,3] row_mask:0xf bank_mask:0xc
	v_mov_b32_dpp v93, v89 quad_perm:[0,1,2,3] row_mask:0xf bank_mask:0xc
	v_mov_b32_dpp v94, v90 quad_perm:[0,1,2,3] row_mask:0xf bank_mask:0xc
	v_mov_b32_dpp v95, v91 quad_perm:[0,1,2,3] row_mask:0xf bank_mask:0xc
	global_store_dwordx4 v148, v[92:95], s[66:67] nt
	global_store_dwordx4 v149, v[84:87], s[66:67] nt
	s_add_u32 s66, s66, 0x2c000
	s_addc_u32 s67, s67, 0
	v_pk_mul_f32 v[64:65], v[64:65], s[68:69] op_sel_hi:[1,0]
	v_pk_mul_f32 v[66:67], v[66:67], s[68:69] op_sel_hi:[1,0]
	v_pk_mul_f32 v[68:69], v[68:69], s[68:69] op_sel_hi:[1,0]
	v_pk_mul_f32 v[70:71], v[70:71], s[68:69] op_sel_hi:[1,0]
	v_pk_mul_f32 v[72:73], v[72:73], s[68:69] op_sel_hi:[1,0]
	v_pk_mul_f32 v[74:75], v[74:75], s[68:69] op_sel_hi:[1,0]
	v_pk_mul_f32 v[76:77], v[76:77], s[68:69] op_sel_hi:[1,0]
	v_pk_mul_f32 v[78:79], v[78:79], s[68:69] op_sel_hi:[1,0]
	v_exp_f32_e32 v64, v64
	v_exp_f32_e32 v65, v65
	v_exp_f32_e32 v66, v66
	v_exp_f32_e32 v67, v67
	v_exp_f32_e32 v68, v68
	v_exp_f32_e32 v69, v69
	v_exp_f32_e32 v70, v70
	v_exp_f32_e32 v71, v71
	v_exp_f32_e32 v72, v72
	v_exp_f32_e32 v73, v73
	v_exp_f32_e32 v74, v74
	v_exp_f32_e32 v75, v75
	v_exp_f32_e32 v76, v76
	v_exp_f32_e32 v77, v77
	v_exp_f32_e32 v78, v78
	v_exp_f32_e32 v79, v79
	v_pk_add_f32 v[64:65], v[64:65], 1.0 op_sel_hi:[1,0]
	v_pk_add_f32 v[66:67], v[66:67], 1.0 op_sel_hi:[1,0]
	v_pk_add_f32 v[68:69], v[68:69], 1.0 op_sel_hi:[1,0]
	v_pk_add_f32 v[70:71], v[70:71], 1.0 op_sel_hi:[1,0]
	v_pk_add_f32 v[72:73], v[72:73], 1.0 op_sel_hi:[1,0]
	v_pk_add_f32 v[74:75], v[74:75], 1.0 op_sel_hi:[1,0]
	v_pk_add_f32 v[76:77], v[76:77], 1.0 op_sel_hi:[1,0]
	v_pk_add_f32 v[78:79], v[78:79], 1.0 op_sel_hi:[1,0]
	v_rcp_f32_e32 v64, v64
	v_rcp_f32_e32 v65, v65
	v_rcp_f32_e32 v66, v66
	v_rcp_f32_e32 v67, v67
	v_rcp_f32_e32 v68, v68
	v_rcp_f32_e32 v69, v69
	v_rcp_f32_e32 v70, v70
	v_rcp_f32_e32 v71, v71
	v_rcp_f32_e32 v72, v72
	v_rcp_f32_e32 v73, v73
	v_rcp_f32_e32 v74, v74
	v_rcp_f32_e32 v75, v75
	v_rcp_f32_e32 v76, v76
	v_rcp_f32_e32 v77, v77
	v_rcp_f32_e32 v78, v78
	v_rcp_f32_e32 v79, v79
	v_cvt_pk_bf16_f32 v76, v76, v77
	v_cvt_pk_bf16_f32 v77, v78, v79
	v_cvt_pk_bf16_f32 v78, v72, v73
	v_cvt_pk_bf16_f32 v79, v74, v75
	v_cvt_pk_bf16_f32 v68, v68, v69
	v_cvt_pk_bf16_f32 v69, v70, v71
	v_cvt_pk_bf16_f32 v70, v64, v65
	v_cvt_pk_bf16_f32 v71, v66, v67
	v_mov_b32_dpp v72, v68 row_ror:8 row_mask:0xf bank_mask:0xf
	v_mov_b32_dpp v73, v69 row_ror:8 row_mask:0xf bank_mask:0xf
	v_mov_b32_dpp v74, v70 row_ror:8 row_mask:0xf bank_mask:0xf
	v_mov_b32_dpp v75, v71 row_ror:8 row_mask:0xf bank_mask:0xf
	v_mov_b32_dpp v68, v76 row_ror:8 row_mask:0xf bank_mask:0x3
	v_mov_b32_dpp v69, v77 row_ror:8 row_mask:0xf bank_mask:0x3
	v_mov_b32_dpp v70, v78 row_ror:8 row_mask:0xf bank_mask:0x3
	v_mov_b32_dpp v71, v79 row_ror:8 row_mask:0xf bank_mask:0x3
	v_mov_b32_dpp v76, v72 quad_perm:[0,1,2,3] row_mask:0xf bank_mask:0xc
	v_mov_b32_dpp v77, v73 quad_perm:[0,1,2,3] row_mask:0xf bank_mask:0xc
	v_mov_b32_dpp v78, v74 quad_perm:[0,1,2,3] row_mask:0xf bank_mask:0xc
	v_mov_b32_dpp v79, v75 quad_perm:[0,1,2,3] row_mask:0xf bank_mask:0xc
	global_store_dwordx4 v148, v[76:79], s[66:67] nt
	global_store_dwordx4 v149, v[68:71], s[66:67] nt
	s_add_u32 s66, s66, 0xdc000
	s_addc_u32 s67, s67, 0
	v_pk_mul_f32 v[48:49], v[48:49], s[68:69] op_sel_hi:[1,0]
	v_pk_mul_f32 v[50:51], v[50:51], s[68:69] op_sel_hi:[1,0]
	v_pk_mul_f32 v[52:53], v[52:53], s[68:69] op_sel_hi:[1,0]
	v_pk_mul_f32 v[54:55], v[54:55], s[68:69] op_sel_hi:[1,0]
	v_pk_mul_f32 v[56:57], v[56:57], s[68:69] op_sel_hi:[1,0]
	v_pk_mul_f32 v[58:59], v[58:59], s[68:69] op_sel_hi:[1,0]
	v_pk_mul_f32 v[60:61], v[60:61], s[68:69] op_sel_hi:[1,0]
	v_pk_mul_f32 v[62:63], v[62:63], s[68:69] op_sel_hi:[1,0]
	v_exp_f32_e32 v48, v48
	v_exp_f32_e32 v49, v49
	v_exp_f32_e32 v50, v50
	v_exp_f32_e32 v51, v51
	v_exp_f32_e32 v52, v52
	v_exp_f32_e32 v53, v53
	v_exp_f32_e32 v54, v54
	v_exp_f32_e32 v55, v55
	v_exp_f32_e32 v56, v56
	v_exp_f32_e32 v57, v57
	v_exp_f32_e32 v58, v58
	v_exp_f32_e32 v59, v59
	v_exp_f32_e32 v60, v60
	v_exp_f32_e32 v61, v61
	v_exp_f32_e32 v62, v62
	v_exp_f32_e32 v63, v63
	v_pk_add_f32 v[48:49], v[48:49], 1.0 op_sel_hi:[1,0]
	v_pk_add_f32 v[50:51], v[50:51], 1.0 op_sel_hi:[1,0]
	v_pk_add_f32 v[52:53], v[52:53], 1.0 op_sel_hi:[1,0]
	v_pk_add_f32 v[54:55], v[54:55], 1.0 op_sel_hi:[1,0]
	v_pk_add_f32 v[56:57], v[56:57], 1.0 op_sel_hi:[1,0]
	v_pk_add_f32 v[58:59], v[58:59], 1.0 op_sel_hi:[1,0]
	v_pk_add_f32 v[60:61], v[60:61], 1.0 op_sel_hi:[1,0]
	v_pk_add_f32 v[62:63], v[62:63], 1.0 op_sel_hi:[1,0]
	v_rcp_f32_e32 v48, v48
	v_rcp_f32_e32 v49, v49
	v_rcp_f32_e32 v50, v50
	v_rcp_f32_e32 v51, v51
	v_rcp_f32_e32 v52, v52
	v_rcp_f32_e32 v53, v53
	v_rcp_f32_e32 v54, v54
	v_rcp_f32_e32 v55, v55
	v_rcp_f32_e32 v56, v56
	v_rcp_f32_e32 v57, v57
	v_rcp_f32_e32 v58, v58
	v_rcp_f32_e32 v59, v59
	v_rcp_f32_e32 v60, v60
	v_rcp_f32_e32 v61, v61
	v_rcp_f32_e32 v62, v62
	v_rcp_f32_e32 v63, v63
	v_cvt_pk_bf16_f32 v60, v60, v61
	v_cvt_pk_bf16_f32 v61, v62, v63
	v_cvt_pk_bf16_f32 v62, v56, v57
	v_cvt_pk_bf16_f32 v63, v58, v59
	v_cvt_pk_bf16_f32 v52, v52, v53
	v_cvt_pk_bf16_f32 v53, v54, v55
	v_cvt_pk_bf16_f32 v54, v48, v49
	v_cvt_pk_bf16_f32 v55, v50, v51
	v_mov_b32_dpp v56, v52 row_ror:8 row_mask:0xf bank_mask:0xf
	v_mov_b32_dpp v57, v53 row_ror:8 row_mask:0xf bank_mask:0xf
	v_mov_b32_dpp v58, v54 row_ror:8 row_mask:0xf bank_mask:0xf
	v_mov_b32_dpp v59, v55 row_ror:8 row_mask:0xf bank_mask:0xf
	v_mov_b32_dpp v52, v60 row_ror:8 row_mask:0xf bank_mask:0x3
	v_mov_b32_dpp v53, v61 row_ror:8 row_mask:0xf bank_mask:0x3
	v_mov_b32_dpp v54, v62 row_ror:8 row_mask:0xf bank_mask:0x3
	v_mov_b32_dpp v55, v63 row_ror:8 row_mask:0xf bank_mask:0x3
	v_mov_b32_dpp v60, v56 quad_perm:[0,1,2,3] row_mask:0xf bank_mask:0xc
	v_mov_b32_dpp v61, v57 quad_perm:[0,1,2,3] row_mask:0xf bank_mask:0xc
	v_mov_b32_dpp v62, v58 quad_perm:[0,1,2,3] row_mask:0xf bank_mask:0xc
	v_mov_b32_dpp v63, v59 quad_perm:[0,1,2,3] row_mask:0xf bank_mask:0xc
	global_store_dwordx4 v148, v[60:63], s[66:67] nt
	global_store_dwordx4 v149, v[52:55], s[66:67] nt
	s_add_u32 s66, s66, 0x2c000
	s_addc_u32 s67, s67, 0
	v_pk_mul_f32 v[32:33], v[32:33], s[68:69] op_sel_hi:[1,0]
	v_pk_mul_f32 v[34:35], v[34:35], s[68:69] op_sel_hi:[1,0]
	v_pk_mul_f32 v[36:37], v[36:37], s[68:69] op_sel_hi:[1,0]
	v_pk_mul_f32 v[38:39], v[38:39], s[68:69] op_sel_hi:[1,0]
	v_pk_mul_f32 v[40:41], v[40:41], s[68:69] op_sel_hi:[1,0]
	v_pk_mul_f32 v[42:43], v[42:43], s[68:69] op_sel_hi:[1,0]
	v_pk_mul_f32 v[44:45], v[44:45], s[68:69] op_sel_hi:[1,0]
	v_pk_mul_f32 v[46:47], v[46:47], s[68:69] op_sel_hi:[1,0]
	v_exp_f32_e32 v32, v32
	v_exp_f32_e32 v33, v33
	v_exp_f32_e32 v34, v34
	v_exp_f32_e32 v35, v35
	v_exp_f32_e32 v36, v36
	v_exp_f32_e32 v37, v37
	v_exp_f32_e32 v38, v38
	v_exp_f32_e32 v39, v39
	v_exp_f32_e32 v40, v40
	v_exp_f32_e32 v41, v41
	v_exp_f32_e32 v42, v42
	v_exp_f32_e32 v43, v43
	v_exp_f32_e32 v44, v44
	v_exp_f32_e32 v45, v45
	v_exp_f32_e32 v46, v46
	v_exp_f32_e32 v47, v47
	v_pk_add_f32 v[32:33], v[32:33], 1.0 op_sel_hi:[1,0]
	v_pk_add_f32 v[34:35], v[34:35], 1.0 op_sel_hi:[1,0]
	v_pk_add_f32 v[36:37], v[36:37], 1.0 op_sel_hi:[1,0]
	v_pk_add_f32 v[38:39], v[38:39], 1.0 op_sel_hi:[1,0]
	v_pk_add_f32 v[40:41], v[40:41], 1.0 op_sel_hi:[1,0]
	v_pk_add_f32 v[42:43], v[42:43], 1.0 op_sel_hi:[1,0]
	v_pk_add_f32 v[44:45], v[44:45], 1.0 op_sel_hi:[1,0]
	v_pk_add_f32 v[46:47], v[46:47], 1.0 op_sel_hi:[1,0]
	v_rcp_f32_e32 v32, v32
	v_rcp_f32_e32 v33, v33
	v_rcp_f32_e32 v34, v34
	v_rcp_f32_e32 v35, v35
	v_rcp_f32_e32 v36, v36
	v_rcp_f32_e32 v37, v37
	v_rcp_f32_e32 v38, v38
	v_rcp_f32_e32 v39, v39
	v_rcp_f32_e32 v40, v40
	v_rcp_f32_e32 v41, v41
	v_rcp_f32_e32 v42, v42
	v_rcp_f32_e32 v43, v43
	v_rcp_f32_e32 v44, v44
	v_rcp_f32_e32 v45, v45
	v_rcp_f32_e32 v46, v46
	v_rcp_f32_e32 v47, v47
	v_cvt_pk_bf16_f32 v44, v44, v45
	v_cvt_pk_bf16_f32 v45, v46, v47
	v_cvt_pk_bf16_f32 v46, v40, v41
	v_cvt_pk_bf16_f32 v47, v42, v43
	v_cvt_pk_bf16_f32 v36, v36, v37
	v_cvt_pk_bf16_f32 v37, v38, v39
	v_cvt_pk_bf16_f32 v38, v32, v33
	v_cvt_pk_bf16_f32 v39, v34, v35
	v_mov_b32_dpp v40, v36 row_ror:8 row_mask:0xf bank_mask:0xf
	v_mov_b32_dpp v41, v37 row_ror:8 row_mask:0xf bank_mask:0xf
	v_mov_b32_dpp v42, v38 row_ror:8 row_mask:0xf bank_mask:0xf
	v_mov_b32_dpp v43, v39 row_ror:8 row_mask:0xf bank_mask:0xf
	v_mov_b32_dpp v36, v44 row_ror:8 row_mask:0xf bank_mask:0x3
	v_mov_b32_dpp v37, v45 row_ror:8 row_mask:0xf bank_mask:0x3
	v_mov_b32_dpp v38, v46 row_ror:8 row_mask:0xf bank_mask:0x3
	v_mov_b32_dpp v39, v47 row_ror:8 row_mask:0xf bank_mask:0x3
	v_mov_b32_dpp v44, v40 quad_perm:[0,1,2,3] row_mask:0xf bank_mask:0xc
	v_mov_b32_dpp v45, v41 quad_perm:[0,1,2,3] row_mask:0xf bank_mask:0xc
	v_mov_b32_dpp v46, v42 quad_perm:[0,1,2,3] row_mask:0xf bank_mask:0xc
	v_mov_b32_dpp v47, v43 quad_perm:[0,1,2,3] row_mask:0xf bank_mask:0xc
	global_store_dwordx4 v148, v[44:47], s[66:67] nt
	global_store_dwordx4 v149, v[36:39], s[66:67] nt
	s_add_u32 s66, s66, 0x2c000
	s_addc_u32 s67, s67, 0
	v_pk_mul_f32 v[16:17], v[16:17], s[68:69] op_sel_hi:[1,0]
	v_pk_mul_f32 v[18:19], v[18:19], s[68:69] op_sel_hi:[1,0]
	v_pk_mul_f32 v[20:21], v[20:21], s[68:69] op_sel_hi:[1,0]
	v_pk_mul_f32 v[22:23], v[22:23], s[68:69] op_sel_hi:[1,0]
	v_pk_mul_f32 v[24:25], v[24:25], s[68:69] op_sel_hi:[1,0]
	v_pk_mul_f32 v[26:27], v[26:27], s[68:69] op_sel_hi:[1,0]
	v_pk_mul_f32 v[28:29], v[28:29], s[68:69] op_sel_hi:[1,0]
	v_pk_mul_f32 v[30:31], v[30:31], s[68:69] op_sel_hi:[1,0]
	v_exp_f32_e32 v16, v16
	v_exp_f32_e32 v17, v17
	v_exp_f32_e32 v18, v18
	v_exp_f32_e32 v19, v19
	v_exp_f32_e32 v20, v20
	v_exp_f32_e32 v21, v21
	v_exp_f32_e32 v22, v22
	v_exp_f32_e32 v23, v23
	v_exp_f32_e32 v24, v24
	v_exp_f32_e32 v25, v25
	v_exp_f32_e32 v26, v26
	v_exp_f32_e32 v27, v27
	v_exp_f32_e32 v28, v28
	v_exp_f32_e32 v29, v29
	v_exp_f32_e32 v30, v30
	v_exp_f32_e32 v31, v31
	v_pk_add_f32 v[16:17], v[16:17], 1.0 op_sel_hi:[1,0]
	v_pk_add_f32 v[18:19], v[18:19], 1.0 op_sel_hi:[1,0]
	v_pk_add_f32 v[20:21], v[20:21], 1.0 op_sel_hi:[1,0]
	v_pk_add_f32 v[22:23], v[22:23], 1.0 op_sel_hi:[1,0]
	v_pk_add_f32 v[24:25], v[24:25], 1.0 op_sel_hi:[1,0]
	v_pk_add_f32 v[26:27], v[26:27], 1.0 op_sel_hi:[1,0]
	v_pk_add_f32 v[28:29], v[28:29], 1.0 op_sel_hi:[1,0]
	v_pk_add_f32 v[30:31], v[30:31], 1.0 op_sel_hi:[1,0]
	v_rcp_f32_e32 v16, v16
	v_rcp_f32_e32 v17, v17
	v_rcp_f32_e32 v18, v18
	v_rcp_f32_e32 v19, v19
	v_rcp_f32_e32 v20, v20
	v_rcp_f32_e32 v21, v21
	v_rcp_f32_e32 v22, v22
	v_rcp_f32_e32 v23, v23
	v_rcp_f32_e32 v24, v24
	v_rcp_f32_e32 v25, v25
	v_rcp_f32_e32 v26, v26
	v_rcp_f32_e32 v27, v27
	v_rcp_f32_e32 v28, v28
	v_rcp_f32_e32 v29, v29
	v_rcp_f32_e32 v30, v30
	v_rcp_f32_e32 v31, v31
	v_cvt_pk_bf16_f32 v28, v28, v29
	v_cvt_pk_bf16_f32 v29, v30, v31
	v_cvt_pk_bf16_f32 v30, v24, v25
	v_cvt_pk_bf16_f32 v31, v26, v27
	v_cvt_pk_bf16_f32 v20, v20, v21
	v_cvt_pk_bf16_f32 v21, v22, v23
	v_cvt_pk_bf16_f32 v22, v16, v17
	v_cvt_pk_bf16_f32 v23, v18, v19
	v_mov_b32_dpp v24, v20 row_ror:8 row_mask:0xf bank_mask:0xf
	v_mov_b32_dpp v25, v21 row_ror:8 row_mask:0xf bank_mask:0xf
	v_mov_b32_dpp v26, v22 row_ror:8 row_mask:0xf bank_mask:0xf
	v_mov_b32_dpp v27, v23 row_ror:8 row_mask:0xf bank_mask:0xf
	v_mov_b32_dpp v20, v28 row_ror:8 row_mask:0xf bank_mask:0x3
	v_mov_b32_dpp v21, v29 row_ror:8 row_mask:0xf bank_mask:0x3
	v_mov_b32_dpp v22, v30 row_ror:8 row_mask:0xf bank_mask:0x3
	v_mov_b32_dpp v23, v31 row_ror:8 row_mask:0xf bank_mask:0x3
	v_mov_b32_dpp v28, v24 quad_perm:[0,1,2,3] row_mask:0xf bank_mask:0xc
	v_mov_b32_dpp v29, v25 quad_perm:[0,1,2,3] row_mask:0xf bank_mask:0xc
	v_mov_b32_dpp v30, v26 quad_perm:[0,1,2,3] row_mask:0xf bank_mask:0xc
	v_mov_b32_dpp v31, v27 quad_perm:[0,1,2,3] row_mask:0xf bank_mask:0xc
	global_store_dwordx4 v148, v[28:31], s[66:67] nt
	global_store_dwordx4 v149, v[20:23], s[66:67] nt
	s_add_u32 s66, s66, 0x2c000
	s_addc_u32 s67, s67, 0
	v_pk_mul_f32 v[0:1], v[0:1], s[68:69] op_sel_hi:[1,0]
	v_pk_mul_f32 v[2:3], v[2:3], s[68:69] op_sel_hi:[1,0]
	v_pk_mul_f32 v[4:5], v[4:5], s[68:69] op_sel_hi:[1,0]
	v_pk_mul_f32 v[6:7], v[6:7], s[68:69] op_sel_hi:[1,0]
	v_pk_mul_f32 v[8:9], v[8:9], s[68:69] op_sel_hi:[1,0]
	v_pk_mul_f32 v[10:11], v[10:11], s[68:69] op_sel_hi:[1,0]
	v_pk_mul_f32 v[12:13], v[12:13], s[68:69] op_sel_hi:[1,0]
	v_pk_mul_f32 v[14:15], v[14:15], s[68:69] op_sel_hi:[1,0]
	v_exp_f32_e32 v0, v0
	v_exp_f32_e32 v1, v1
	v_exp_f32_e32 v2, v2
	v_exp_f32_e32 v3, v3
	v_exp_f32_e32 v4, v4
	v_exp_f32_e32 v5, v5
	v_exp_f32_e32 v6, v6
	v_exp_f32_e32 v7, v7
	v_exp_f32_e32 v8, v8
	v_exp_f32_e32 v9, v9
	v_exp_f32_e32 v10, v10
	v_exp_f32_e32 v11, v11
	v_exp_f32_e32 v12, v12
	v_exp_f32_e32 v13, v13
	v_exp_f32_e32 v14, v14
	v_exp_f32_e32 v15, v15
	v_pk_add_f32 v[0:1], v[0:1], 1.0 op_sel_hi:[1,0]
	v_pk_add_f32 v[2:3], v[2:3], 1.0 op_sel_hi:[1,0]
	v_pk_add_f32 v[4:5], v[4:5], 1.0 op_sel_hi:[1,0]
	v_pk_add_f32 v[6:7], v[6:7], 1.0 op_sel_hi:[1,0]
	v_pk_add_f32 v[8:9], v[8:9], 1.0 op_sel_hi:[1,0]
	v_pk_add_f32 v[10:11], v[10:11], 1.0 op_sel_hi:[1,0]
	v_pk_add_f32 v[12:13], v[12:13], 1.0 op_sel_hi:[1,0]
	v_pk_add_f32 v[14:15], v[14:15], 1.0 op_sel_hi:[1,0]
	v_rcp_f32_e32 v0, v0
	v_rcp_f32_e32 v1, v1
	v_rcp_f32_e32 v2, v2
	v_rcp_f32_e32 v3, v3
	v_rcp_f32_e32 v4, v4
	v_rcp_f32_e32 v5, v5
	v_rcp_f32_e32 v6, v6
	v_rcp_f32_e32 v7, v7
	v_rcp_f32_e32 v8, v8
	v_rcp_f32_e32 v9, v9
	v_rcp_f32_e32 v10, v10
	v_rcp_f32_e32 v11, v11
	v_rcp_f32_e32 v12, v12
	v_rcp_f32_e32 v13, v13
	v_rcp_f32_e32 v14, v14
	v_rcp_f32_e32 v15, v15
	v_cvt_pk_bf16_f32 v12, v12, v13
	v_cvt_pk_bf16_f32 v13, v14, v15
	v_cvt_pk_bf16_f32 v14, v8, v9
	v_cvt_pk_bf16_f32 v15, v10, v11
	v_cvt_pk_bf16_f32 v4, v4, v5
	v_cvt_pk_bf16_f32 v5, v6, v7
	v_cvt_pk_bf16_f32 v6, v0, v1
	v_cvt_pk_bf16_f32 v7, v2, v3
	v_mov_b32_dpp v8, v4 row_ror:8 row_mask:0xf bank_mask:0xf
	v_mov_b32_dpp v9, v5 row_ror:8 row_mask:0xf bank_mask:0xf
	v_mov_b32_dpp v10, v6 row_ror:8 row_mask:0xf bank_mask:0xf
	v_mov_b32_dpp v11, v7 row_ror:8 row_mask:0xf bank_mask:0xf
	v_mov_b32_dpp v4, v12 row_ror:8 row_mask:0xf bank_mask:0x3
	v_mov_b32_dpp v5, v13 row_ror:8 row_mask:0xf bank_mask:0x3
	v_mov_b32_dpp v6, v14 row_ror:8 row_mask:0xf bank_mask:0x3
	v_mov_b32_dpp v7, v15 row_ror:8 row_mask:0xf bank_mask:0x3
	v_mov_b32_dpp v12, v8 quad_perm:[0,1,2,3] row_mask:0xf bank_mask:0xc
	v_mov_b32_dpp v13, v9 quad_perm:[0,1,2,3] row_mask:0xf bank_mask:0xc
	v_mov_b32_dpp v14, v10 quad_perm:[0,1,2,3] row_mask:0xf bank_mask:0xc
	v_mov_b32_dpp v15, v11 quad_perm:[0,1,2,3] row_mask:0xf bank_mask:0xc
	global_store_dwordx4 v148, v[12:15], s[66:67] nt
	global_store_dwordx4 v149, v[4:7], s[66:67] nt
